# adds hand-scheduled hgrn16 latent scan body (LDS prefetch, batched y reduction) on top of previous version
# speedup vs baseline: 1.0307x; 1.0031x over previous
.LBB0_437:
	s_andn2_b64 vcc, exec, vcc
	s_bitcmp1_b32 s46, 0
	s_cselect_b32 s46, 0x6000, 0
	s_add_i32 s46, s78, s46
	v_lshl_add_u32 v98, v24, 2, s46
	v_lshl_add_u32 v31, v23, 4, s46
	v_add_u32_e32 v98, 0x5000, v98
	v_and_b32_e32 v99, 1, v23
	v_and_b32_e32 v100, 2, v23
	ds_read_b128 v[40:43], v31 offset:8192
	ds_read_b32 v44, v98 offset:0
	ds_read_b128 v[36:39], v31 offset:4096
	ds_read_b128 v[32:35], v31 offset:0
	v_cmp_ne_u32_e64 s[4:5], 0, v99
	v_cmp_ne_u32_e64 s[6:7], 0, v100
	ds_read_b128 v[56:59], v31 offset:8448
	ds_read_b32 v60, v98 offset:64
	ds_read_b128 v[52:55], v31 offset:4352
	ds_read_b128 v[48:51], v31 offset:256
	s_waitcnt lgkmcnt(4)
	v_pk_mul_f32 v[62:63], v[40:41], v[44:45] op_sel_hi:[1,0]
	v_pk_mul_f32 v[64:65], v[42:43], v[44:45] op_sel_hi:[1,0]
	v_pk_fma_f32 v[16:17], v[16:17], v[36:37], v[62:63]
	v_pk_fma_f32 v[14:15], v[14:15], v[38:39], v[64:65]
	v_mul_f32_e32 v66, v33, v17
	v_fmac_f32_e32 v66, v32, v16
	v_fmac_f32_e32 v66, v34, v14
	v_fmac_f32_e32 v66, v35, v15
	ds_read_b128 v[40:43], v31 offset:8704
	ds_read_b32 v44, v98 offset:128
	ds_read_b128 v[36:39], v31 offset:4608
	ds_read_b128 v[32:35], v31 offset:512
	s_waitcnt lgkmcnt(4)
	v_pk_mul_f32 v[62:63], v[56:57], v[60:61] op_sel_hi:[1,0]
	v_pk_mul_f32 v[64:65], v[58:59], v[60:61] op_sel_hi:[1,0]
	v_pk_fma_f32 v[16:17], v[16:17], v[52:53], v[62:63]
	v_pk_fma_f32 v[14:15], v[14:15], v[54:55], v[64:65]
	v_mul_f32_e32 v67, v49, v17
	v_fmac_f32_e32 v67, v48, v16
	v_fmac_f32_e32 v67, v50, v14
	v_fmac_f32_e32 v67, v51, v15
	ds_read_b128 v[56:59], v31 offset:8960
	ds_read_b32 v60, v98 offset:192
	ds_read_b128 v[52:55], v31 offset:4864
	ds_read_b128 v[48:51], v31 offset:768
	s_waitcnt lgkmcnt(4)
	v_pk_mul_f32 v[62:63], v[40:41], v[44:45] op_sel_hi:[1,0]
	v_pk_mul_f32 v[64:65], v[42:43], v[44:45] op_sel_hi:[1,0]
	v_pk_fma_f32 v[16:17], v[16:17], v[36:37], v[62:63]
	v_pk_fma_f32 v[14:15], v[14:15], v[38:39], v[64:65]
	v_mul_f32_e32 v68, v33, v17
	v_fmac_f32_e32 v68, v32, v16
	v_fmac_f32_e32 v68, v34, v14
	v_fmac_f32_e32 v68, v35, v15
	ds_read_b128 v[40:43], v31 offset:9216
	ds_read_b32 v44, v98 offset:256
	ds_read_b128 v[36:39], v31 offset:5120
	ds_read_b128 v[32:35], v31 offset:1024
	s_waitcnt lgkmcnt(4)
	v_pk_mul_f32 v[62:63], v[56:57], v[60:61] op_sel_hi:[1,0]
	v_pk_mul_f32 v[64:65], v[58:59], v[60:61] op_sel_hi:[1,0]
	v_pk_fma_f32 v[16:17], v[16:17], v[52:53], v[62:63]
	v_pk_fma_f32 v[14:15], v[14:15], v[54:55], v[64:65]
	v_mul_f32_e32 v69, v49, v17
	v_fmac_f32_e32 v69, v48, v16
	v_fmac_f32_e32 v69, v50, v14
	v_fmac_f32_e32 v69, v51, v15
	ds_read_b128 v[56:59], v31 offset:9472
	ds_read_b32 v60, v98 offset:320
	ds_read_b128 v[52:55], v31 offset:5376
	ds_read_b128 v[48:51], v31 offset:1280
	s_waitcnt lgkmcnt(4)
	v_pk_mul_f32 v[62:63], v[40:41], v[44:45] op_sel_hi:[1,0]
	v_pk_mul_f32 v[64:65], v[42:43], v[44:45] op_sel_hi:[1,0]
	v_pk_fma_f32 v[16:17], v[16:17], v[36:37], v[62:63]
	v_pk_fma_f32 v[14:15], v[14:15], v[38:39], v[64:65]
	v_mul_f32_e32 v70, v33, v17
	v_fmac_f32_e32 v70, v32, v16
	v_fmac_f32_e32 v70, v34, v14
	v_fmac_f32_e32 v70, v35, v15
	ds_read_b128 v[40:43], v31 offset:9728
	ds_read_b32 v44, v98 offset:384
	ds_read_b128 v[36:39], v31 offset:5632
	ds_read_b128 v[32:35], v31 offset:1536
	s_waitcnt lgkmcnt(4)
	v_pk_mul_f32 v[62:63], v[56:57], v[60:61] op_sel_hi:[1,0]
	v_pk_mul_f32 v[64:65], v[58:59], v[60:61] op_sel_hi:[1,0]
	v_pk_fma_f32 v[16:17], v[16:17], v[52:53], v[62:63]
	v_pk_fma_f32 v[14:15], v[14:15], v[54:55], v[64:65]
	v_mul_f32_e32 v71, v49, v17
	v_fmac_f32_e32 v71, v48, v16
	v_fmac_f32_e32 v71, v50, v14
	v_fmac_f32_e32 v71, v51, v15
	ds_read_b128 v[56:59], v31 offset:9984
	ds_read_b32 v60, v98 offset:448
	ds_read_b128 v[52:55], v31 offset:5888
	ds_read_b128 v[48:51], v31 offset:1792
	s_waitcnt lgkmcnt(4)
	v_pk_mul_f32 v[62:63], v[40:41], v[44:45] op_sel_hi:[1,0]
	v_pk_mul_f32 v[64:65], v[42:43], v[44:45] op_sel_hi:[1,0]
	v_pk_fma_f32 v[16:17], v[16:17], v[36:37], v[62:63]
	v_pk_fma_f32 v[14:15], v[14:15], v[38:39], v[64:65]
	v_mul_f32_e32 v72, v33, v17
	v_fmac_f32_e32 v72, v32, v16
	v_fmac_f32_e32 v72, v34, v14
	v_fmac_f32_e32 v72, v35, v15
	ds_read_b128 v[40:43], v31 offset:10240
	ds_read_b32 v44, v98 offset:512
	ds_read_b128 v[36:39], v31 offset:6144
	ds_read_b128 v[32:35], v31 offset:2048
	s_waitcnt lgkmcnt(4)
	v_pk_mul_f32 v[62:63], v[56:57], v[60:61] op_sel_hi:[1,0]
	v_pk_mul_f32 v[64:65], v[58:59], v[60:61] op_sel_hi:[1,0]
	v_pk_fma_f32 v[16:17], v[16:17], v[52:53], v[62:63]
	v_pk_fma_f32 v[14:15], v[14:15], v[54:55], v[64:65]
	v_mul_f32_e32 v73, v49, v17
	v_fmac_f32_e32 v73, v48, v16
	v_fmac_f32_e32 v73, v50, v14
	v_fmac_f32_e32 v73, v51, v15
	ds_read_b128 v[56:59], v31 offset:10496
	ds_read_b32 v60, v98 offset:576
	ds_read_b128 v[52:55], v31 offset:6400
	ds_read_b128 v[48:51], v31 offset:2304
	s_waitcnt lgkmcnt(4)
	v_pk_mul_f32 v[62:63], v[40:41], v[44:45] op_sel_hi:[1,0]
	v_pk_mul_f32 v[64:65], v[42:43], v[44:45] op_sel_hi:[1,0]
	v_pk_fma_f32 v[16:17], v[16:17], v[36:37], v[62:63]
	v_pk_fma_f32 v[14:15], v[14:15], v[38:39], v[64:65]
	v_mul_f32_e32 v74, v33, v17
	v_fmac_f32_e32 v74, v32, v16
	v_fmac_f32_e32 v74, v34, v14
	v_fmac_f32_e32 v74, v35, v15
	ds_read_b128 v[40:43], v31 offset:10752
	ds_read_b32 v44, v98 offset:640
	ds_read_b128 v[36:39], v31 offset:6656
	ds_read_b128 v[32:35], v31 offset:2560
	s_waitcnt lgkmcnt(4)
	v_pk_mul_f32 v[62:63], v[56:57], v[60:61] op_sel_hi:[1,0]
	v_pk_mul_f32 v[64:65], v[58:59], v[60:61] op_sel_hi:[1,0]
	v_pk_fma_f32 v[16:17], v[16:17], v[52:53], v[62:63]
	v_pk_fma_f32 v[14:15], v[14:15], v[54:55], v[64:65]
	v_mul_f32_e32 v75, v49, v17
	v_fmac_f32_e32 v75, v48, v16
	v_fmac_f32_e32 v75, v50, v14
	v_fmac_f32_e32 v75, v51, v15
	ds_read_b128 v[56:59], v31 offset:11008
	ds_read_b32 v60, v98 offset:704
	ds_read_b128 v[52:55], v31 offset:6912
	ds_read_b128 v[48:51], v31 offset:2816
	s_waitcnt lgkmcnt(4)
	v_pk_mul_f32 v[62:63], v[40:41], v[44:45] op_sel_hi:[1,0]
	v_pk_mul_f32 v[64:65], v[42:43], v[44:45] op_sel_hi:[1,0]
	v_pk_fma_f32 v[16:17], v[16:17], v[36:37], v[62:63]
	v_pk_fma_f32 v[14:15], v[14:15], v[38:39], v[64:65]
	v_mul_f32_e32 v76, v33, v17
	v_fmac_f32_e32 v76, v32, v16
	v_fmac_f32_e32 v76, v34, v14
	v_fmac_f32_e32 v76, v35, v15
	ds_read_b128 v[40:43], v31 offset:11264
	ds_read_b32 v44, v98 offset:768
	ds_read_b128 v[36:39], v31 offset:7168
	ds_read_b128 v[32:35], v31 offset:3072
	s_waitcnt lgkmcnt(4)
	v_pk_mul_f32 v[62:63], v[56:57], v[60:61] op_sel_hi:[1,0]
	v_pk_mul_f32 v[64:65], v[58:59], v[60:61] op_sel_hi:[1,0]
	v_pk_fma_f32 v[16:17], v[16:17], v[52:53], v[62:63]
	v_pk_fma_f32 v[14:15], v[14:15], v[54:55], v[64:65]
	v_mul_f32_e32 v77, v49, v17
	v_fmac_f32_e32 v77, v48, v16
	v_fmac_f32_e32 v77, v50, v14
	v_fmac_f32_e32 v77, v51, v15
	ds_read_b128 v[56:59], v31 offset:11520
	ds_read_b32 v60, v98 offset:832
	ds_read_b128 v[52:55], v31 offset:7424
	ds_read_b128 v[48:51], v31 offset:3328
	s_waitcnt lgkmcnt(4)
	v_pk_mul_f32 v[62:63], v[40:41], v[44:45] op_sel_hi:[1,0]
	v_pk_mul_f32 v[64:65], v[42:43], v[44:45] op_sel_hi:[1,0]
	v_pk_fma_f32 v[16:17], v[16:17], v[36:37], v[62:63]
	v_pk_fma_f32 v[14:15], v[14:15], v[38:39], v[64:65]
	v_mul_f32_e32 v78, v33, v17
	v_fmac_f32_e32 v78, v32, v16
	v_fmac_f32_e32 v78, v34, v14
	v_fmac_f32_e32 v78, v35, v15
	ds_read_b128 v[40:43], v31 offset:11776
	ds_read_b32 v44, v98 offset:896
	ds_read_b128 v[36:39], v31 offset:7680
	ds_read_b128 v[32:35], v31 offset:3584
	s_waitcnt lgkmcnt(4)
	v_pk_mul_f32 v[62:63], v[56:57], v[60:61] op_sel_hi:[1,0]
	v_pk_mul_f32 v[64:65], v[58:59], v[60:61] op_sel_hi:[1,0]
	v_pk_fma_f32 v[16:17], v[16:17], v[52:53], v[62:63]
	v_pk_fma_f32 v[14:15], v[14:15], v[54:55], v[64:65]
	v_mul_f32_e32 v79, v49, v17
	v_fmac_f32_e32 v79, v48, v16
	v_fmac_f32_e32 v79, v50, v14
	v_fmac_f32_e32 v79, v51, v15
	ds_read_b128 v[56:59], v31 offset:12032
	ds_read_b32 v60, v98 offset:960
	ds_read_b128 v[52:55], v31 offset:7936
	ds_read_b128 v[48:51], v31 offset:3840
	s_waitcnt lgkmcnt(4)
	v_pk_mul_f32 v[62:63], v[40:41], v[44:45] op_sel_hi:[1,0]
	v_pk_mul_f32 v[64:65], v[42:43], v[44:45] op_sel_hi:[1,0]
	v_pk_fma_f32 v[16:17], v[16:17], v[36:37], v[62:63]
	v_pk_fma_f32 v[14:15], v[14:15], v[38:39], v[64:65]
	v_mul_f32_e32 v80, v33, v17
	v_fmac_f32_e32 v80, v32, v16
	v_fmac_f32_e32 v80, v34, v14
	v_fmac_f32_e32 v80, v35, v15
	s_waitcnt lgkmcnt(0)
	v_pk_mul_f32 v[62:63], v[56:57], v[60:61] op_sel_hi:[1,0]
	v_pk_mul_f32 v[64:65], v[58:59], v[60:61] op_sel_hi:[1,0]
	v_pk_fma_f32 v[16:17], v[16:17], v[52:53], v[62:63]
	v_pk_fma_f32 v[14:15], v[14:15], v[54:55], v[64:65]
	v_mul_f32_e32 v81, v49, v17
	v_fmac_f32_e32 v81, v48, v16
	v_fmac_f32_e32 v81, v50, v14
	v_fmac_f32_e32 v81, v51, v15
	v_cndmask_b32_e64 v82, v66, v67, s[4:5]
	v_cndmask_b32_e64 v90, v67, v66, s[4:5]
	v_cndmask_b32_e64 v83, v68, v69, s[4:5]
	v_cndmask_b32_e64 v91, v69, v68, s[4:5]
	v_cndmask_b32_e64 v84, v70, v71, s[4:5]
	v_cndmask_b32_e64 v92, v71, v70, s[4:5]
	v_cndmask_b32_e64 v85, v72, v73, s[4:5]
	v_cndmask_b32_e64 v93, v73, v72, s[4:5]
	v_cndmask_b32_e64 v86, v74, v75, s[4:5]
	v_cndmask_b32_e64 v94, v75, v74, s[4:5]
	v_cndmask_b32_e64 v87, v76, v77, s[4:5]
	v_cndmask_b32_e64 v95, v77, v76, s[4:5]
	v_cndmask_b32_e64 v88, v78, v79, s[4:5]
	v_cndmask_b32_e64 v96, v79, v78, s[4:5]
	v_cndmask_b32_e64 v89, v80, v81, s[4:5]
	v_cndmask_b32_e64 v97, v81, v80, s[4:5]
	v_add_f32_dpp v66, v90, v82 quad_perm:[1,0,3,2] row_mask:0xf bank_mask:0xf bound_ctrl:1
	v_add_f32_dpp v67, v91, v83 quad_perm:[1,0,3,2] row_mask:0xf bank_mask:0xf bound_ctrl:1
	v_add_f32_dpp v68, v92, v84 quad_perm:[1,0,3,2] row_mask:0xf bank_mask:0xf bound_ctrl:1
	v_add_f32_dpp v69, v93, v85 quad_perm:[1,0,3,2] row_mask:0xf bank_mask:0xf bound_ctrl:1
	v_add_f32_dpp v70, v94, v86 quad_perm:[1,0,3,2] row_mask:0xf bank_mask:0xf bound_ctrl:1
	v_add_f32_dpp v71, v95, v87 quad_perm:[1,0,3,2] row_mask:0xf bank_mask:0xf bound_ctrl:1
	v_add_f32_dpp v72, v96, v88 quad_perm:[1,0,3,2] row_mask:0xf bank_mask:0xf bound_ctrl:1
	v_add_f32_dpp v73, v97, v89 quad_perm:[1,0,3,2] row_mask:0xf bank_mask:0xf bound_ctrl:1
	v_cndmask_b32_e64 v82, v66, v67, s[6:7]
	v_cndmask_b32_e64 v90, v67, v66, s[6:7]
	v_cndmask_b32_e64 v83, v68, v69, s[6:7]
	v_cndmask_b32_e64 v91, v69, v68, s[6:7]
	v_cndmask_b32_e64 v84, v70, v71, s[6:7]
	v_cndmask_b32_e64 v92, v71, v70, s[6:7]
	v_cndmask_b32_e64 v85, v72, v73, s[6:7]
	v_cndmask_b32_e64 v93, v73, v72, s[6:7]
	v_add_f32_dpp v74, v90, v82 quad_perm:[2,3,0,1] row_mask:0xf bank_mask:0xf bound_ctrl:1
	v_add_f32_dpp v75, v91, v83 quad_perm:[2,3,0,1] row_mask:0xf bank_mask:0xf bound_ctrl:1
	v_add_f32_dpp v76, v92, v84 quad_perm:[2,3,0,1] row_mask:0xf bank_mask:0xf bound_ctrl:1
	v_add_f32_dpp v77, v93, v85 quad_perm:[2,3,0,1] row_mask:0xf bank_mask:0xf bound_ctrl:1
	s_nop 0
	v_add_f32_dpp v78, v74, v74 row_shl:4 row_mask:0xf bank_mask:0x5 bound_ctrl:1
	v_add_f32_dpp v79, v76, v76 row_shl:4 row_mask:0xf bank_mask:0x5 bound_ctrl:1
	s_nop 0
	v_add_f32_dpp v78, v75, v75 row_shr:4 row_mask:0xf bank_mask:0xa bound_ctrl:1
	v_add_f32_dpp v79, v77, v77 row_shr:4 row_mask:0xf bank_mask:0xa bound_ctrl:1
	s_nop 1
	v_add_f32_dpp v31, v78, v78 row_shl:8 row_mask:0xf bank_mask:0x3 bound_ctrl:1
	s_nop 1
	v_add_f32_dpp v31, v79, v79 row_shr:8 row_mask:0xf bank_mask:0xc bound_ctrl:1
	v_cndmask_b32_e64 v32, v27, v30, s[0:1]
	v_add_u32_e32 v32, s82, v32
	v_ashrrev_i32_e32 v33, 31, v32
	v_lshlrev_b64 v[32:33], 10, v[32:33]
	v_lshl_add_u64 v[32:33], v[18:19], 0, v[32:33]
	global_store_dword v[32:33], v31, off
	s_cbranch_vccnz .LBB0_439
	s_waitcnt vmcnt(2)
	v_lshlrev_b32_e32 v31, 16, v8
	v_mul_f32_e32 v31, 0xbfb8aa3b, v31
	v_exp_f32_e32 v31, v31
	v_lshlrev_b32_e32 v32, 16, v6
	v_and_b32_e32 v33, 0xffff0000, v6
	v_mul_f32_e32 v40, 0xbfb8aa3b, v32
	v_add_f32_e32 v31, 1.0, v31
	v_rcp_f32_e32 v36, v31
	v_and_b32_e32 v31, 0xffff0000, v8
	v_mul_f32_e32 v31, 0xbfb8aa3b, v31
	v_exp_f32_e32 v31, v31
	v_mul_f32_e32 v41, 0xbfb8aa3b, v33
	v_exp_f32_e32 v40, v40
	v_exp_f32_e32 v41, v41
	v_add_f32_e32 v31, 1.0, v31
	v_rcp_f32_e32 v37, v31
	v_lshlrev_b32_e32 v31, 16, v9
	v_mul_f32_e32 v31, 0xbfb8aa3b, v31
	v_exp_f32_e32 v31, v31
	v_add_f32_e32 v40, 1.0, v40
	v_add_f32_e32 v41, 1.0, v41
	v_rcp_f32_e32 v40, v40
	v_rcp_f32_e32 v41, v41
	v_lshlrev_b32_e32 v34, 16, v7
	v_and_b32_e32 v35, 0xffff0000, v7
	v_add_f32_e32 v31, 1.0, v31
	v_rcp_f32_e32 v38, v31
	v_and_b32_e32 v31, 0xffff0000, v9
	v_pk_mul_f32 v[32:33], v[40:41], v[32:33]
	v_mul_f32_e32 v40, 0xbfb8aa3b, v34
	v_mul_f32_e32 v41, 0xbfb8aa3b, v35
	v_mul_f32_e32 v31, 0xbfb8aa3b, v31
	v_exp_f32_e32 v40, v40
	v_exp_f32_e32 v41, v41
	v_exp_f32_e32 v31, v31
	s_bitcmp1_b32 s47, 0
	v_add_f32_e32 v40, 1.0, v40
	v_add_f32_e32 v41, 1.0, v41
	v_add_f32_e32 v31, 1.0, v31
	v_rcp_f32_e32 v40, v40
	v_rcp_f32_e32 v41, v41
	v_rcp_f32_e32 v39, v31
	s_cselect_b32 s46, 0x6000, 0
	s_add_i32 s46, s78, s46
	v_lshl_add_u32 v31, v22, 4, s46
	v_pk_mul_f32 v[34:35], v[40:41], v[34:35]
	ds_write_b128 v31, v[32:35]
	v_lshl_add_u32 v40, v25, 4, s46
	v_pk_fma_f32 v[32:33], v[10:11], v[36:37], v[0:1]
	v_pk_fma_f32 v[34:35], v[12:13], v[38:39], v[2:3]
	ds_write_b128 v40, v[32:35] offset:4096
	v_pk_add_f32 v[32:33], v[36:37], 1.0 op_sel_hi:[1,0] neg_lo:[1,0] neg_hi:[1,0]
	v_pk_add_f32 v[34:35], v[38:39], 1.0 op_sel_hi:[1,0] neg_lo:[1,0] neg_hi:[1,0]
	v_pk_mul_f32 v[32:33], v[10:11], v[32:33]
	v_pk_mul_f32 v[34:35], v[12:13], v[34:35]
	ds_write_b128 v40, v[32:35] offset:8192
	s_waitcnt vmcnt(1)
	v_lshlrev_b32_e32 v32, 16, v21
	v_add_u32_e32 v31, v31, v26
	ds_write_b32 v31, v32 offset:20480
